# attention bias-minus-rowmax block packed (v_pk_add_f32 with pre-negated row max), on top of v19
# baseline (speedup 1.0000x reference)
; #define WAIT_BAR(N) asm volatile("s_waitcnt vmcnt(" #N ") lgkmcnt(0)\n\ts_barrier":::"memory")
;   #define DMA_K(t,slot) glds16(ksrc+(long)(t)*KVBLK*DM,(unsigned)__builtin_amdgcn_readfirstlane(kdst+(slot)))
;   #define DMA_V(t,slot) glds16(vsrc+(long)(t)*KVBLK*DM,(unsigned)__builtin_amdgcn_readfirstlane(vdst+(slot)))
;   #define BIAS(C0,C1,t) do{ const lds_cptr tb_=tb0+256*(t); \
;     _Pragma("unroll") for(int g_=0;g_<4;++g_){ const f32x4_t v0_=*(tab_ptr)(tb_+32*g_), v1_=*(tab_ptr)(tb_+32*g_+128); \
;       C0[4*g_]=v0_[0]-mhat;C0[4*g_+1]=v0_[1]-mhat;C0[4*g_+2]=v0_[2]-mhat;C0[4*g_+3]=v0_[3]-mhat; \
;       C1[4*g_]=v1_[0]-mhat;C1[4*g_+1]=v1_[1]-mhat;C1[4*g_+2]=v1_[2]-mhat;C1[4*g_+3]=v1_[3]-mhat; } }while(0)
;   #define START(P0,P1) do{ const float rm=rowmax(P0,P1); resc=false; \
;     { const float dl=rm; mhat=fadd_s(mhat,dl); \
;       _Pragma("unroll") for(int r=0;r<16;++r){P0[r]=fsub_s(P0[r],dl);P1[r]=fsub_s(P1[r],dl);} \
;       } \
;     _Pragma("unroll") for(int r=0;r<16;++r)P0[r]=__builtin_amdgcn_exp2f(P0[r]); }while(0)
;   #define ROT() do{sl_prev=sl_cur;sl_cur=sl_next;sl_next=(sl_next==(NSLOT-1)*SLOTB)?0:sl_next+SLOTB;}while(0)
; template<int THRL> __device__ __forceinline__ void attn_unit(int b,int h,int qb,const bf16*Q,const bf16*__restrict__ K,const bf16*__restrict__ V,bf16*O,float*SSQA,char*shm){
;     ...
;   const int qrel=wid*QBLK+r32;
;   bool resc=false;
;     ...
;   f32x16 pA0,pA1,pB0,pB1;
;   int sl_prev=0,sl_cur=0,sl_next=SLOTB;
;     ...
;   DMA_K(2,2*SLOTB);
;   WAIT_BAR(3);
;   BIAS(pA0,pA1,0); qkt(pA0,pA1,Kbase,qr,r32,hi);asm volatile("s_nop 15\n\ts_nop 7":"+v"(pA0),"+v"(pA1));
;   START(pA0,pA1);
;   _Pragma("unroll") for(int r=0;r<16;++r)pA1[r]=__builtin_amdgcn_exp2f(pA1[r]);
;   WAIT_BAR(0);
;   DMA_K(3,0);DMA_V(1,SLOTB);
;   ROT();
;   kload8(kf,kp0+sl_cur);
;   WAIT_BAR(2);
;   s16x4 vlo[8],vhi[8]; u32x4 pw0,pw1,pw2,pw3;
.LBB0_484:
	ds_read_b128 v[2:5], v186
	ds_read_b128 v[6:9], v186 offset:32
	ds_read_b128 v[10:13], v186 offset:64
	ds_read_b128 v[80:83], v186 offset:96
	ds_read_b128 v[216:219], v186 offset:128
	ds_read_b128 v[84:87], v186 offset:160
	ds_read_b128 v[88:91], v186 offset:192
	ds_read_b128 v[92:95], v186 offset:224
	s_waitcnt lgkmcnt(4)
	v_xor_b32_e32 v240, 0x80000000, v201
	v_pk_add_f32 v[110:111], v[82:83], v[240:241] op_sel_hi:[1,0]
	v_pk_add_f32 v[108:109], v[80:81], v[240:241] op_sel_hi:[1,0]
	v_pk_add_f32 v[106:107], v[12:13], v[240:241] op_sel_hi:[1,0]
	v_pk_add_f32 v[104:105], v[10:11], v[240:241] op_sel_hi:[1,0]
	v_pk_add_f32 v[102:103], v[8:9], v[240:241] op_sel_hi:[1,0]
	v_pk_add_f32 v[100:101], v[6:7], v[240:241] op_sel_hi:[1,0]
	v_pk_add_f32 v[98:99], v[4:5], v[240:241] op_sel_hi:[1,0]
	v_pk_add_f32 v[96:97], v[2:3], v[240:241] op_sel_hi:[1,0]
	s_waitcnt lgkmcnt(0)
	v_pk_add_f32 v[94:95], v[94:95], v[240:241] op_sel_hi:[1,0]
	v_pk_add_f32 v[92:93], v[92:93], v[240:241] op_sel_hi:[1,0]
	v_pk_add_f32 v[90:91], v[90:91], v[240:241] op_sel_hi:[1,0]
	v_pk_add_f32 v[88:89], v[88:89], v[240:241] op_sel_hi:[1,0]
	v_pk_add_f32 v[86:87], v[86:87], v[240:241] op_sel_hi:[1,0]
	v_pk_add_f32 v[84:85], v[84:85], v[240:241] op_sel_hi:[1,0]
	v_pk_add_f32 v[82:83], v[218:219], v[240:241] op_sel_hi:[1,0]
	v_pk_add_f32 v[80:81], v[216:217], v[240:241] op_sel_hi:[1,0]
	v_add_u32_e32 v1, s6, v199
	ds_read_b64_tr_b16 v[2:3], v1 offset:24576
	ds_read_b64_tr_b16 v[4:5], v1 offset:25088
	v_mfma_f32_32x32x16_bf16 v[96:111], v[172:175], v[132:135], v[96:111]
	v_add_f32_e32 v6, v64, v65
	v_add_f32_e32 v6, v66, v6
	v_add_f32_e32 v6, v67, v6
	v_add_f32_e32 v6, v68, v6
	v_add_f32_e32 v10, v69, v6
	v_cvt_pk_bf16_f32 v140, v64, v65
	v_cvt_pk_bf16_f32 v141, v66, v67
	ds_read_b64_tr_b16 v[6:7], v1 offset:28672
	ds_read_b64_tr_b16 v[8:9], v1 offset:29184
	v_mfma_f32_32x32x16_bf16 v[80:95], v[168:171], v[132:135], v[80:95]
	v_add_f32_e32 v10, v70, v10
	v_add_f32_e32 v10, v71, v10
	v_add_f32_e32 v10, v72, v10
	v_add_f32_e32 v14, v73, v10
	v_cvt_pk_bf16_f32 v142, v68, v69
	v_cvt_pk_bf16_f32 v143, v70, v71
	ds_read_b64_tr_b16 v[10:11], v1 offset:25600
	ds_read_b64_tr_b16 v[12:13], v1 offset:26112
	v_mfma_f32_32x32x16_bf16 v[96:111], v[164:167], v[120:123], v[96:111]
	v_add_f32_e32 v14, v74, v14
	v_add_f32_e32 v14, v75, v14
	v_add_f32_e32 v14, v76, v14
	v_add_f32_e32 v14, v77, v14
	v_cvt_pk_bf16_f32 v136, v72, v73
	v_cvt_pk_bf16_f32 v137, v74, v75
	ds_read_b64_tr_b16 v[64:65], v1 offset:29696
	ds_read_b64_tr_b16 v[66:67], v1 offset:30208
	v_mfma_f32_32x32x16_bf16 v[80:95], v[160:163], v[120:123], v[80:95]
	v_add_f32_e32 v14, v78, v14
	v_add_f32_e32 v14, v79, v14
	v_add_f32_e32 v14, v48, v14
	v_add_f32_e32 v14, v49, v14
	v_cvt_pk_bf16_f32 v138, v76, v77
	v_cvt_pk_bf16_f32 v139, v78, v79
	ds_read_b64_tr_b16 v[68:69], v1 offset:26624
	ds_read_b64_tr_b16 v[70:71], v1 offset:27136
	v_mfma_f32_32x32x16_bf16 v[96:111], v[156:159], v[116:119], v[96:111]
	v_add_f32_e32 v14, v50, v14
	v_add_f32_e32 v14, v51, v14
	v_add_f32_e32 v14, v52, v14
	v_add_f32_e32 v14, v53, v14
	v_cvt_pk_bf16_f32 v128, v48, v49
	v_cvt_pk_bf16_f32 v129, v50, v51
	ds_read_b64_tr_b16 v[48:49], v1 offset:30720
	ds_read_b64_tr_b16 v[50:51], v1 offset:31232
	v_mfma_f32_32x32x16_bf16 v[80:95], v[152:155], v[116:119], v[80:95]
	v_add_f32_e32 v14, v54, v14
	v_add_f32_e32 v14, v55, v14
	v_add_f32_e32 v14, v56, v14
	v_add_f32_e32 v14, v57, v14
	v_cvt_pk_bf16_f32 v130, v52, v53
	v_cvt_pk_bf16_f32 v131, v54, v55
	ds_read_b64_tr_b16 v[52:53], v1 offset:27648
	ds_read_b64_tr_b16 v[54:55], v1 offset:28160
	v_mfma_f32_32x32x16_bf16 v[96:111], v[148:151], v[112:115], v[96:111]
	v_add_f32_e32 v14, v58, v14
	v_add_f32_e32 v14, v59, v14
	v_add_f32_e32 v14, v60, v14
	v_add_f32_e32 v14, v61, v14
	v_cvt_pk_bf16_f32 v124, v56, v57
	v_cvt_pk_bf16_f32 v125, v58, v59
	ds_read_b64_tr_b16 v[56:57], v1 offset:31744
	ds_read_b64_tr_b16 v[58:59], v1 offset:32256
	v_mfma_f32_32x32x16_bf16 v[80:95], v[144:147], v[112:115], v[80:95]
	v_add_f32_e32 v1, v62, v14
	v_add_f32_e32 v1, v63, v1
	v_add_f32_e32 v1, 0, v1
	v_cvt_pk_bf16_f32 v126, v60, v61
	v_cvt_pk_bf16_f32 v127, v62, v63
	v_lshl_add_u64 v[14:15], v[182:183], 0, s[58:59]
	s_add_i32 s6, s18, s39
	s_mov_b32 s7, m0
	s_mov_b32 m0, s6
	s_nop 0
	global_load_lds_dwordx4 v[14:15], off
	s_mov_b32 m0, s7
	v_lshl_add_u64 v[14:15], v[180:181], 0, s[58:59]
	s_add_i32 s6, s14, s42
	s_mov_b32 s7, m0
	s_mov_b32 m0, s6
	s_nop 0
	global_load_lds_dwordx4 v[14:15], off
	s_mov_b32 m0, s7
	v_max_f32_e32 v14, v97, v97
	v_max_f32_e32 v15, v96, v96
	v_max_f32_e32 v14, v15, v14
	v_max3_f32 v15, v98, v99, v81
	v_max3_f32 v14, v14, v80, v82
	v_max3_f32 v14, v14, v83, v100
	v_max3_f32 v15, v15, v102, v103
	v_max3_f32 v14, v14, v101, v84
	v_max3_f32 v15, v15, v86, v87
	v_max3_f32 v14, v14, v85, v104
	v_max3_f32 v15, v15, v106, v107
	v_max3_f32 v14, v14, v105, v88
	v_max3_f32 v15, v15, v90, v91
	v_max3_f32 v14, v14, v89, v108
	v_max3_f32 v15, v15, v110, v111
	v_max3_f32 v14, v14, v109, v92
	v_max3_f32 v15, v15, v94, v95
	v_max3_f32 v14, v14, v93, v15
	v_mov_b32_e32 v15, v14
	s_nop 1
	v_permlane32_swap_b32_e32 v14, v15
	v_max_f32_e32 v15, v15, v15
	v_max_f32_e32 v14, v14, v14
	v_max_f32_e32 v14, v14, v15
	v_cmp_lt_f32_e32 vcc, s96, v14
	s_cmp_lg_u64 vcc, 0
	v_add_f32_e32 v1, v203, v1
	s_cselect_b64 s[6:7], -1, 0
	s_cbranch_vccnz .LBB0_492

; #define WAIT_BAR(N) asm volatile("s_waitcnt vmcnt(" #N ") lgkmcnt(0)\n\ts_barrier":::"memory")
;   #define DMA_K(t,slot) glds16(ksrc+(long)(t)*KVBLK*DM,(unsigned)__builtin_amdgcn_readfirstlane(kdst+(slot)))
;   #define DMA_V(t,slot) glds16(vsrc+(long)(t)*KVBLK*DM,(unsigned)__builtin_amdgcn_readfirstlane(vdst+(slot)))
;   #define BIAS(C0,C1,t) do{ const lds_cptr tb_=tb0+256*(t); \
;     _Pragma("unroll") for(int g_=0;g_<4;++g_){ const f32x4_t v0_=*(tab_ptr)(tb_+32*g_), v1_=*(tab_ptr)(tb_+32*g_+128); \
;       C0[4*g_]=v0_[0]-mhat;C0[4*g_+1]=v0_[1]-mhat;C0[4*g_+2]=v0_[2]-mhat;C0[4*g_+3]=v0_[3]-mhat; \
;       C1[4*g_]=v1_[0]-mhat;C1[4*g_+1]=v1_[1]-mhat;C1[4*g_+2]=v1_[2]-mhat;C1[4*g_+3]=v1_[3]-mhat; } }while(0)
;   #define START(P0,P1) do{ const float rm=rowmax(P0,P1); resc=false; \
;     { const float dl=rm; mhat=fadd_s(mhat,dl); \
;       _Pragma("unroll") for(int r=0;r<16;++r){P0[r]=fsub_s(P0[r],dl);P1[r]=fsub_s(P1[r],dl);} \
;       } \
;     _Pragma("unroll") for(int r=0;r<16;++r)P0[r]=__builtin_amdgcn_exp2f(P0[r]); }while(0)
;   #define ROT() do{sl_prev=sl_cur;sl_cur=sl_next;sl_next=(sl_next==(NSLOT-1)*SLOTB)?0:sl_next+SLOTB;}while(0)
; template<int THRL> __device__ __forceinline__ void attn_unit(int b,int h,int qb,const bf16*Q,const bf16*__restrict__ K,const bf16*__restrict__ V,bf16*O,float*SSQA,char*shm){
;     ...
;   const int qrel=wid*QBLK+r32;
;   bool resc=false;
;     ...
;   f32x16 pA0,pA1,pB0,pB1;
;   int sl_prev=0,sl_cur=0,sl_next=SLOTB;
;     ...
;   DMA_K(2,2*SLOTB);
;   WAIT_BAR(3);
;   BIAS(pA0,pA1,0); qkt(pA0,pA1,Kbase,qr,r32,hi);asm volatile("s_nop 15\n\ts_nop 7":"+v"(pA0),"+v"(pA1));
;   START(pA0,pA1);
;   _Pragma("unroll") for(int r=0;r<16;++r)pA1[r]=__builtin_amdgcn_exp2f(pA1[r]);
;   WAIT_BAR(0);
;   DMA_K(3,0);DMA_V(1,SLOTB);
;   ROT();
;   kload8(kf,kp0+sl_cur);
;   WAIT_BAR(2);
;   s16x4 vlo[8],vhi[8]; u32x4 pw0,pw1,pw2,pw3;
.LBB0_487:
	s_add_i32 s6, s14, 0x2000
	ds_read_b128 v[48:51], v186 offset:256
	ds_read_b128 v[52:55], v186 offset:288
	ds_read_b128 v[56:59], v186 offset:320
	ds_read_b128 v[60:63], v186 offset:352
	ds_read_b128 v[160:163], v186 offset:384
	ds_read_b128 v[168:171], v186 offset:416
	ds_read_b128 v[172:175], v186 offset:448
	ds_read_b128 v[216:219], v186 offset:480
	s_cmpk_lg_i32 s14, 0x4000
	s_waitcnt lgkmcnt(4)
	v_xor_b32_e32 v240, 0x80000000, v201
	v_pk_add_f32 v[78:79], v[62:63], v[240:241] op_sel_hi:[1,0]
	v_pk_add_f32 v[76:77], v[60:61], v[240:241] op_sel_hi:[1,0]
	v_pk_add_f32 v[74:75], v[58:59], v[240:241] op_sel_hi:[1,0]
	v_pk_add_f32 v[72:73], v[56:57], v[240:241] op_sel_hi:[1,0]
	v_pk_add_f32 v[70:71], v[54:55], v[240:241] op_sel_hi:[1,0]
	v_pk_add_f32 v[68:69], v[52:53], v[240:241] op_sel_hi:[1,0]
	v_pk_add_f32 v[66:67], v[50:51], v[240:241] op_sel_hi:[1,0]
	v_pk_add_f32 v[64:65], v[48:49], v[240:241] op_sel_hi:[1,0]
	s_waitcnt lgkmcnt(0)
	v_pk_add_f32 v[62:63], v[218:219], v[240:241] op_sel_hi:[1,0]
	v_pk_add_f32 v[60:61], v[216:217], v[240:241] op_sel_hi:[1,0]
	v_pk_add_f32 v[58:59], v[174:175], v[240:241] op_sel_hi:[1,0]
	v_pk_add_f32 v[56:57], v[172:173], v[240:241] op_sel_hi:[1,0]
	v_pk_add_f32 v[54:55], v[170:171], v[240:241] op_sel_hi:[1,0]
	v_pk_add_f32 v[52:53], v[168:169], v[240:241] op_sel_hi:[1,0]
	v_pk_add_f32 v[50:51], v[162:163], v[240:241] op_sel_hi:[1,0]
	v_pk_add_f32 v[48:49], v[160:161], v[240:241] op_sel_hi:[1,0]
	s_cselect_b32 s62, s6, 0
	v_add_u32_e32 v14, s18, v199
	ds_read_b64_tr_b16 v[160:161], v14 offset:24576
	ds_read_b64_tr_b16 v[162:163], v14 offset:25088
	v_mfma_f32_32x32x16_bf16 v[64:79], v[164:167], v[132:135], v[64:79]
	v_add_f32_e32 v15, v96, v97
	v_add_f32_e32 v15, v98, v15
	v_add_f32_e32 v15, v99, v15
	v_add_f32_e32 v15, v100, v15
	v_add_f32_e32 v15, v101, v15
	v_cvt_pk_bf16_f32 v140, v96, v97
	v_cvt_pk_bf16_f32 v141, v98, v99
	ds_read_b64_tr_b16 v[96:97], v14 offset:28672
	ds_read_b64_tr_b16 v[98:99], v14 offset:29184
	v_mfma_f32_32x32x16_bf16 v[48:63], v[156:159], v[132:135], v[48:63]
	v_add_f32_e32 v15, v102, v15
	v_add_f32_e32 v15, v103, v15
	v_add_f32_e32 v15, v104, v15
	v_add_f32_e32 v15, v105, v15
	v_cvt_pk_bf16_f32 v142, v100, v101
	v_cvt_pk_bf16_f32 v143, v102, v103
	ds_read_b64_tr_b16 v[100:101], v14 offset:25600
	ds_read_b64_tr_b16 v[102:103], v14 offset:26112
	v_mfma_f32_32x32x16_bf16 v[64:79], v[152:155], v[120:123], v[64:79]
	v_add_f32_e32 v15, v106, v15
	v_add_f32_e32 v15, v107, v15
	v_add_f32_e32 v15, v108, v15
	v_add_f32_e32 v15, v109, v15
	v_cvt_pk_bf16_f32 v136, v104, v105
	v_cvt_pk_bf16_f32 v137, v106, v107
	ds_read_b64_tr_b16 v[104:105], v14 offset:29696
	ds_read_b64_tr_b16 v[106:107], v14 offset:30208
	v_mfma_f32_32x32x16_bf16 v[48:63], v[148:151], v[120:123], v[48:63]
	v_add_f32_e32 v15, v110, v15
	v_add_f32_e32 v15, v111, v15
	v_add_f32_e32 v15, v80, v15
	v_add_f32_e32 v15, v81, v15
	v_cvt_pk_bf16_f32 v138, v108, v109
	v_cvt_pk_bf16_f32 v139, v110, v111
	ds_read_b64_tr_b16 v[108:109], v14 offset:26624
	ds_read_b64_tr_b16 v[110:111], v14 offset:27136
	v_mfma_f32_32x32x16_bf16 v[64:79], v[144:147], v[116:119], v[64:79]
	v_add_f32_e32 v15, v82, v15
	v_add_f32_e32 v15, v83, v15
	v_add_f32_e32 v15, v84, v15
	v_add_f32_e32 v15, v85, v15
	v_cvt_pk_bf16_f32 v128, v80, v81
	v_cvt_pk_bf16_f32 v129, v82, v83
	ds_read_b64_tr_b16 v[80:81], v14 offset:30720
	ds_read_b64_tr_b16 v[82:83], v14 offset:31232
	v_mfma_f32_32x32x16_bf16 v[48:63], v[10:13], v[116:119], v[48:63]
	v_add_f32_e32 v15, v86, v15
	v_add_f32_e32 v15, v87, v15
	v_add_f32_e32 v15, v88, v15
	v_add_f32_e32 v15, v89, v15
	v_cvt_pk_bf16_f32 v130, v84, v85
	v_cvt_pk_bf16_f32 v131, v86, v87
	ds_read_b64_tr_b16 v[10:11], v14 offset:27648
	ds_read_b64_tr_b16 v[12:13], v14 offset:28160
	v_mfma_f32_32x32x16_bf16 v[64:79], v[6:9], v[112:115], v[64:79]
	v_add_f32_e32 v15, v90, v15
	v_add_f32_e32 v15, v91, v15
	v_add_f32_e32 v15, v92, v15
	v_add_f32_e32 v15, v93, v15
	v_cvt_pk_bf16_f32 v124, v88, v89
	v_cvt_pk_bf16_f32 v125, v90, v91
	ds_read_b64_tr_b16 v[6:7], v14 offset:31744
	ds_read_b64_tr_b16 v[8:9], v14 offset:32256
	v_mfma_f32_32x32x16_bf16 v[48:63], v[2:5], v[112:115], v[48:63]
	v_add_f32_e32 v14, v94, v15
	v_add_f32_e32 v14, v95, v14
	v_add_f32_e32 v14, 0, v14
	v_cvt_pk_bf16_f32 v126, v92, v93
	v_cvt_pk_bf16_f32 v127, v94, v95
	v_max_f32_e32 v2, v65, v65
	v_max_f32_e32 v3, v64, v64
	v_max_f32_e32 v2, v3, v2
	s_nop 3
	v_max3_f32 v3, v66, v67, v49
	v_max3_f32 v2, v2, v48, v50
	v_max3_f32 v2, v2, v51, v68
	v_max3_f32 v3, v3, v70, v71
	v_max3_f32 v2, v2, v69, v52
	v_max3_f32 v3, v3, v54, v55
	v_max3_f32 v2, v2, v53, v72
	v_max3_f32 v3, v3, v74, v75
	v_max3_f32 v2, v2, v73, v56
	v_max3_f32 v3, v3, v58, v59
	v_max3_f32 v2, v2, v57, v76
	v_max3_f32 v3, v3, v78, v79
	v_max3_f32 v2, v2, v77, v60
	v_max3_f32 v3, v3, v62, v63
	v_add_f32_e32 v203, v1, v14
	v_max3_f32 v1, v2, v61, v3
	v_mov_b32_e32 v2, v1
	s_nop 1
	v_permlane32_swap_b32_e32 v1, v2
	v_max_f32_e32 v2, v2, v2
	v_max_f32_e32 v1, v1, v1
	s_add_i32 s6, s14, s39
	s_mov_b32 s7, m0
	s_mov_b32 m0, s6
	s_nop 0
	global_load_lds_dwordx4 v[182:183], off
	s_mov_b32 m0, s7
	v_max_f32_e32 v1, v1, v2
	s_add_i32 s6, s62, s42
	s_mov_b32 s7, m0
	s_mov_b32 m0, s6
	s_nop 0
	global_load_lds_dwordx4 v[180:181], off
	s_mov_b32 m0, s7
	v_cmp_lt_f32_e32 vcc, s96, v1
	s_cmp_lg_u64 vcc, 0
	s_cselect_b64 s[6:7], -1, 0
	s_cbranch_vccnz .LBB0_495

; #define WAIT_BAR(N) asm volatile("s_waitcnt vmcnt(" #N ") lgkmcnt(0)\n\ts_barrier":::"memory")
;   #define DMA_K(t,slot) glds16(ksrc+(long)(t)*KVBLK*DM,(unsigned)__builtin_amdgcn_readfirstlane(kdst+(slot)))
;   #define DMA_V(t,slot) glds16(vsrc+(long)(t)*KVBLK*DM,(unsigned)__builtin_amdgcn_readfirstlane(vdst+(slot)))
;   #define BIAS(C0,C1,t) do{ const lds_cptr tb_=tb0+256*(t); \
;     _Pragma("unroll") for(int g_=0;g_<4;++g_){ const f32x4_t v0_=*(tab_ptr)(tb_+32*g_), v1_=*(tab_ptr)(tb_+32*g_+128); \
;       C0[4*g_]=v0_[0]-mhat;C0[4*g_+1]=v0_[1]-mhat;C0[4*g_+2]=v0_[2]-mhat;C0[4*g_+3]=v0_[3]-mhat; \
;       C1[4*g_]=v1_[0]-mhat;C1[4*g_+1]=v1_[1]-mhat;C1[4*g_+2]=v1_[2]-mhat;C1[4*g_+3]=v1_[3]-mhat; } }while(0)
;   #define START(P0,P1) do{ const float rm=rowmax(P0,P1); resc=false; \
;     { const float dl=rm; mhat=fadd_s(mhat,dl); \
;       _Pragma("unroll") for(int r=0;r<16;++r){P0[r]=fsub_s(P0[r],dl);P1[r]=fsub_s(P1[r],dl);} \
;       } \
;     _Pragma("unroll") for(int r=0;r<16;++r)P0[r]=__builtin_amdgcn_exp2f(P0[r]); }while(0)
;   #define ROT() do{sl_prev=sl_cur;sl_cur=sl_next;sl_next=(sl_next==(NSLOT-1)*SLOTB)?0:sl_next+SLOTB;}while(0)
; template<int THRL> __device__ __forceinline__ void attn_unit(int b,int h,int qb,const bf16*Q,const bf16*__restrict__ K,const bf16*__restrict__ V,bf16*O,float*SSQA,char*shm){
;     ...
;   const int qrel=wid*QBLK+r32;
;   bool resc=false;
;     ...
;   f32x16 pA0,pA1,pB0,pB1;
;   int sl_prev=0,sl_cur=0,sl_next=SLOTB;
;     ...
;   DMA_K(2,2*SLOTB);
;   WAIT_BAR(3);
;   BIAS(pA0,pA1,0); qkt(pA0,pA1,Kbase,qr,r32,hi);asm volatile("s_nop 15\n\ts_nop 7":"+v"(pA0),"+v"(pA1));
;   START(pA0,pA1);
;   _Pragma("unroll") for(int r=0;r<16;++r)pA1[r]=__builtin_amdgcn_exp2f(pA1[r]);
;   WAIT_BAR(0);
;   DMA_K(3,0);DMA_V(1,SLOTB);
;   ROT();
;   kload8(kf,kp0+sl_cur);
;   WAIT_BAR(2);
;   s16x4 vlo[8],vhi[8]; u32x4 pw0,pw1,pw2,pw3;
.LBB0_501:
	ds_read_b128 v[2:5], v1
	ds_read_b128 v[6:9], v1 offset:32
	ds_read_b128 v[10:13], v1 offset:64
	ds_read_b128 v[80:83], v1 offset:96
	ds_read_b128 v[176:179], v1 offset:128
	ds_read_b128 v[84:87], v1 offset:160
	ds_read_b128 v[88:91], v1 offset:192
	ds_read_b128 v[92:95], v1 offset:224
	s_waitcnt lgkmcnt(4)
	v_xor_b32_e32 v240, 0x80000000, v201
	v_pk_add_f32 v[110:111], v[82:83], v[240:241] op_sel_hi:[1,0]
	v_pk_add_f32 v[108:109], v[80:81], v[240:241] op_sel_hi:[1,0]
	v_pk_add_f32 v[106:107], v[12:13], v[240:241] op_sel_hi:[1,0]
	v_pk_add_f32 v[104:105], v[10:11], v[240:241] op_sel_hi:[1,0]
	v_pk_add_f32 v[102:103], v[8:9], v[240:241] op_sel_hi:[1,0]
	v_pk_add_f32 v[100:101], v[6:7], v[240:241] op_sel_hi:[1,0]
	v_pk_add_f32 v[98:99], v[4:5], v[240:241] op_sel_hi:[1,0]
	v_pk_add_f32 v[96:97], v[2:3], v[240:241] op_sel_hi:[1,0]
	s_waitcnt lgkmcnt(0)
	v_pk_add_f32 v[94:95], v[94:95], v[240:241] op_sel_hi:[1,0]
	v_pk_add_f32 v[92:93], v[92:93], v[240:241] op_sel_hi:[1,0]
	v_pk_add_f32 v[90:91], v[90:91], v[240:241] op_sel_hi:[1,0]
	v_pk_add_f32 v[88:89], v[88:89], v[240:241] op_sel_hi:[1,0]
	v_pk_add_f32 v[86:87], v[86:87], v[240:241] op_sel_hi:[1,0]
	v_pk_add_f32 v[84:85], v[84:85], v[240:241] op_sel_hi:[1,0]
	v_pk_add_f32 v[82:83], v[178:179], v[240:241] op_sel_hi:[1,0]
	v_pk_add_f32 v[80:81], v[176:177], v[240:241] op_sel_hi:[1,0]
	v_add_u32_e32 v176, s14, v199
	ds_read_b64_tr_b16 v[2:3], v176 offset:24576
	ds_read_b64_tr_b16 v[4:5], v176 offset:25088
	v_mfma_f32_32x32x16_bf16 v[96:111], v[172:175], v[132:135], v[96:111]
	v_add_f32_e32 v6, v64, v65
	v_add_f32_e32 v6, v66, v6
	v_add_f32_e32 v6, v67, v6
	v_add_f32_e32 v6, v68, v6
	v_add_f32_e32 v10, v69, v6
	v_cvt_pk_bf16_f32 v140, v64, v65
	v_cvt_pk_bf16_f32 v141, v66, v67
	ds_read_b64_tr_b16 v[6:7], v176 offset:28672
	ds_read_b64_tr_b16 v[8:9], v176 offset:29184
	v_mfma_f32_32x32x16_bf16 v[80:95], v[168:171], v[132:135], v[80:95]
	v_add_f32_e32 v10, v70, v10
	v_add_f32_e32 v10, v71, v10
	v_add_f32_e32 v10, v72, v10
	v_add_f32_e32 v64, v73, v10
	v_cvt_pk_bf16_f32 v142, v68, v69
	v_cvt_pk_bf16_f32 v143, v70, v71
	ds_read_b64_tr_b16 v[10:11], v176 offset:25600
	ds_read_b64_tr_b16 v[12:13], v176 offset:26112
	v_mfma_f32_32x32x16_bf16 v[96:111], v[164:167], v[120:123], v[96:111]
	v_add_f32_e32 v64, v74, v64
	v_add_f32_e32 v64, v75, v64
	v_add_f32_e32 v64, v76, v64
	v_add_f32_e32 v68, v77, v64
	v_cvt_pk_bf16_f32 v136, v72, v73
	v_cvt_pk_bf16_f32 v137, v74, v75
	ds_read_b64_tr_b16 v[64:65], v176 offset:29696
	ds_read_b64_tr_b16 v[66:67], v176 offset:30208
	v_mfma_f32_32x32x16_bf16 v[80:95], v[160:163], v[120:123], v[80:95]
	v_add_f32_e32 v68, v78, v68
	v_add_f32_e32 v68, v79, v68
	v_add_f32_e32 v68, v48, v68
	v_add_f32_e32 v72, v49, v68
	v_cvt_pk_bf16_f32 v138, v76, v77
	v_cvt_pk_bf16_f32 v139, v78, v79
	ds_read_b64_tr_b16 v[68:69], v176 offset:26624
	ds_read_b64_tr_b16 v[70:71], v176 offset:27136
	v_mfma_f32_32x32x16_bf16 v[96:111], v[156:159], v[116:119], v[96:111]
	v_add_f32_e32 v72, v50, v72
	v_add_f32_e32 v72, v51, v72
	v_add_f32_e32 v72, v52, v72
	v_add_f32_e32 v72, v53, v72
	v_cvt_pk_bf16_f32 v128, v48, v49
	v_cvt_pk_bf16_f32 v129, v50, v51
	ds_read_b64_tr_b16 v[48:49], v176 offset:30720
	ds_read_b64_tr_b16 v[50:51], v176 offset:31232
	v_mfma_f32_32x32x16_bf16 v[80:95], v[152:155], v[116:119], v[80:95]
	v_add_f32_e32 v72, v54, v72
	v_add_f32_e32 v72, v55, v72
	v_add_f32_e32 v72, v56, v72
	v_add_f32_e32 v72, v57, v72
	v_cvt_pk_bf16_f32 v130, v52, v53
	v_cvt_pk_bf16_f32 v131, v54, v55
	ds_read_b64_tr_b16 v[52:53], v176 offset:27648
	ds_read_b64_tr_b16 v[54:55], v176 offset:28160
	v_mfma_f32_32x32x16_bf16 v[96:111], v[148:151], v[112:115], v[96:111]
	v_add_f32_e32 v72, v58, v72
	v_add_f32_e32 v72, v59, v72
	v_add_f32_e32 v72, v60, v72
	v_add_f32_e32 v72, v61, v72
	v_cvt_pk_bf16_f32 v124, v56, v57
	v_cvt_pk_bf16_f32 v125, v58, v59
	ds_read_b64_tr_b16 v[56:57], v176 offset:31744
	ds_read_b64_tr_b16 v[58:59], v176 offset:32256
	v_mfma_f32_32x32x16_bf16 v[80:95], v[144:147], v[112:115], v[80:95]
	v_add_f32_e32 v72, v62, v72
	v_add_f32_e32 v72, v63, v72
	v_add_f32_e32 v72, 0, v72
	v_cvt_pk_bf16_f32 v126, v60, v61
	v_cvt_pk_bf16_f32 v127, v62, v63
	s_add_i32 s6, s17, 1
	s_cmp_ge_i32 s6, s61
	s_cselect_b64 s[12:13], -1, 0
	s_and_b64 vcc, exec, s[12:13]
	s_cbranch_vccnz .LBB0_503
	v_lshl_add_u64 v[60:61], v[188:189], 0, s[58:59]
	s_add_i32 s6, s62, s39
	s_mov_b32 s7, m0
	s_mov_b32 m0, s6
	s_nop 0
	global_load_lds_dwordx4 v[60:61], off
	s_mov_b32 m0, s7

; #define WAIT_BAR(N) asm volatile("s_waitcnt vmcnt(" #N ") lgkmcnt(0)\n\ts_barrier":::"memory")
;   #define DMA_K(t,slot) glds16(ksrc+(long)(t)*KVBLK*DM,(unsigned)__builtin_amdgcn_readfirstlane(kdst+(slot)))
;   #define DMA_V(t,slot) glds16(vsrc+(long)(t)*KVBLK*DM,(unsigned)__builtin_amdgcn_readfirstlane(vdst+(slot)))
;   #define BIAS(C0,C1,t) do{ const lds_cptr tb_=tb0+256*(t); \
;     _Pragma("unroll") for(int g_=0;g_<4;++g_){ const f32x4_t v0_=*(tab_ptr)(tb_+32*g_), v1_=*(tab_ptr)(tb_+32*g_+128); \
;       C0[4*g_]=v0_[0]-mhat;C0[4*g_+1]=v0_[1]-mhat;C0[4*g_+2]=v0_[2]-mhat;C0[4*g_+3]=v0_[3]-mhat; \
;       C1[4*g_]=v1_[0]-mhat;C1[4*g_+1]=v1_[1]-mhat;C1[4*g_+2]=v1_[2]-mhat;C1[4*g_+3]=v1_[3]-mhat; } }while(0)
;   #define START(P0,P1) do{ const float rm=rowmax(P0,P1); resc=false; \
;     { const float dl=rm; mhat=fadd_s(mhat,dl); \
;       _Pragma("unroll") for(int r=0;r<16;++r){P0[r]=fsub_s(P0[r],dl);P1[r]=fsub_s(P1[r],dl);} \
;       } \
;     _Pragma("unroll") for(int r=0;r<16;++r)P0[r]=__builtin_amdgcn_exp2f(P0[r]); }while(0)
;   #define ROT() do{sl_prev=sl_cur;sl_cur=sl_next;sl_next=(sl_next==(NSLOT-1)*SLOTB)?0:sl_next+SLOTB;}while(0)
; template<int THRL> __device__ __forceinline__ void attn_unit(int b,int h,int qb,const bf16*Q,const bf16*__restrict__ K,const bf16*__restrict__ V,bf16*O,float*SSQA,char*shm){
;     ...
;   const int qrel=wid*QBLK+r32;
;   bool resc=false;
;     ...
;   f32x16 pA0,pA1,pB0,pB1;
;   int sl_prev=0,sl_cur=0,sl_next=SLOTB;
;     ...
;   DMA_K(2,2*SLOTB);
;   WAIT_BAR(3);
;   BIAS(pA0,pA1,0); qkt(pA0,pA1,Kbase,qr,r32,hi);asm volatile("s_nop 15\n\ts_nop 7":"+v"(pA0),"+v"(pA1));
;   START(pA0,pA1);
;   _Pragma("unroll") for(int r=0;r<16;++r)pA1[r]=__builtin_amdgcn_exp2f(pA1[r]);
;   WAIT_BAR(0);
;   DMA_K(3,0);DMA_V(1,SLOTB);
;   ROT();
;   kload8(kf,kp0+sl_cur);
;   WAIT_BAR(2);
;   s16x4 vlo[8],vhi[8]; u32x4 pw0,pw1,pw2,pw3;
.LBB0_508:
	ds_read_b128 v[2:5], v1 offset:256
	ds_read_b128 v[6:9], v1 offset:288
	ds_read_b128 v[10:13], v1 offset:320
	ds_read_b128 v[48:51], v1 offset:352
	ds_read_b128 v[176:179], v1 offset:384
	ds_read_b128 v[52:55], v1 offset:416
	ds_read_b128 v[56:59], v1 offset:448
	ds_read_b128 v[60:63], v1 offset:480
	s_waitcnt lgkmcnt(4)
	v_xor_b32_e32 v240, 0x80000000, v201
	v_pk_add_f32 v[78:79], v[50:51], v[240:241] op_sel_hi:[1,0]
	v_pk_add_f32 v[76:77], v[48:49], v[240:241] op_sel_hi:[1,0]
	v_pk_add_f32 v[74:75], v[12:13], v[240:241] op_sel_hi:[1,0]
	v_pk_add_f32 v[72:73], v[10:11], v[240:241] op_sel_hi:[1,0]
	v_pk_add_f32 v[70:71], v[8:9], v[240:241] op_sel_hi:[1,0]
	v_pk_add_f32 v[68:69], v[6:7], v[240:241] op_sel_hi:[1,0]
	v_pk_add_f32 v[66:67], v[4:5], v[240:241] op_sel_hi:[1,0]
	v_pk_add_f32 v[64:65], v[2:3], v[240:241] op_sel_hi:[1,0]
	s_waitcnt lgkmcnt(0)
	v_pk_add_f32 v[62:63], v[62:63], v[240:241] op_sel_hi:[1,0]
	v_pk_add_f32 v[60:61], v[60:61], v[240:241] op_sel_hi:[1,0]
	v_pk_add_f32 v[58:59], v[58:59], v[240:241] op_sel_hi:[1,0]
	v_pk_add_f32 v[56:57], v[56:57], v[240:241] op_sel_hi:[1,0]
	v_pk_add_f32 v[54:55], v[54:55], v[240:241] op_sel_hi:[1,0]
	v_pk_add_f32 v[52:53], v[52:53], v[240:241] op_sel_hi:[1,0]
	v_pk_add_f32 v[50:51], v[178:179], v[240:241] op_sel_hi:[1,0]
	v_pk_add_f32 v[48:49], v[176:177], v[240:241] op_sel_hi:[1,0]
	v_add_u32_e32 v4, s62, v199
	ds_read_b64_tr_b16 v[184:185], v4 offset:24576
	ds_read_b64_tr_b16 v[186:187], v4 offset:25088
	v_mfma_f32_32x32x16_bf16 v[64:79], v[172:175], v[132:135], v[64:79]
	v_add_f32_e32 v2, v96, v97
	v_add_f32_e32 v2, v98, v2
	v_add_f32_e32 v2, v99, v2
	v_add_f32_e32 v2, v100, v2
	v_add_f32_e32 v2, v101, v2
	v_cvt_pk_bf16_f32 v140, v96, v97
	v_cvt_pk_bf16_f32 v141, v98, v99
	ds_read_b64_tr_b16 v[180:181], v4 offset:28672
	ds_read_b64_tr_b16 v[182:183], v4 offset:29184
	v_mfma_f32_32x32x16_bf16 v[48:63], v[168:171], v[132:135], v[48:63]
	v_add_f32_e32 v2, v102, v2
	v_add_f32_e32 v2, v103, v2
	v_add_f32_e32 v2, v104, v2
	v_add_f32_e32 v2, v105, v2
	v_cvt_pk_bf16_f32 v142, v100, v101
	v_cvt_pk_bf16_f32 v143, v102, v103
	ds_read_b64_tr_b16 v[176:177], v4 offset:25600
	ds_read_b64_tr_b16 v[178:179], v4 offset:26112
	v_mfma_f32_32x32x16_bf16 v[64:79], v[164:167], v[120:123], v[64:79]
	v_add_f32_e32 v2, v106, v2
	v_add_f32_e32 v2, v107, v2
	v_add_f32_e32 v2, v108, v2
	v_add_f32_e32 v2, v109, v2
	v_cvt_pk_bf16_f32 v136, v104, v105
	v_cvt_pk_bf16_f32 v137, v106, v107
	ds_read_b64_tr_b16 v[100:101], v4 offset:29696
	ds_read_b64_tr_b16 v[102:103], v4 offset:30208
	v_mfma_f32_32x32x16_bf16 v[48:63], v[160:163], v[120:123], v[48:63]
	v_add_f32_e32 v2, v110, v2
	v_add_f32_e32 v2, v111, v2
	v_add_f32_e32 v2, v80, v2
	v_add_f32_e32 v2, v81, v2
	v_cvt_pk_bf16_f32 v138, v108, v109
	v_cvt_pk_bf16_f32 v139, v110, v111
	ds_read_b64_tr_b16 v[96:97], v4 offset:26624
	ds_read_b64_tr_b16 v[98:99], v4 offset:27136
	v_mfma_f32_32x32x16_bf16 v[64:79], v[156:159], v[116:119], v[64:79]
	v_add_f32_e32 v2, v82, v2
	v_add_f32_e32 v2, v83, v2
	v_add_f32_e32 v2, v84, v2
	v_add_f32_e32 v2, v85, v2
	v_cvt_pk_bf16_f32 v128, v80, v81
	v_cvt_pk_bf16_f32 v129, v82, v83
	ds_read_b64_tr_b16 v[10:11], v4 offset:30720
	ds_read_b64_tr_b16 v[12:13], v4 offset:31232
	v_mfma_f32_32x32x16_bf16 v[48:63], v[152:155], v[116:119], v[48:63]
	v_add_f32_e32 v2, v86, v2
	v_add_f32_e32 v2, v87, v2
	v_add_f32_e32 v2, v88, v2
	v_add_f32_e32 v2, v89, v2
	v_cvt_pk_bf16_f32 v130, v84, v85
	v_cvt_pk_bf16_f32 v131, v86, v87
	ds_read_b64_tr_b16 v[6:7], v4 offset:27648
	ds_read_b64_tr_b16 v[8:9], v4 offset:28160
	v_mfma_f32_32x32x16_bf16 v[64:79], v[148:151], v[112:115], v[64:79]
	v_add_f32_e32 v2, v90, v2
	v_add_f32_e32 v2, v91, v2
	v_add_f32_e32 v2, v92, v2
	v_add_f32_e32 v80, v93, v2
	v_cvt_pk_bf16_f32 v124, v88, v89
	v_cvt_pk_bf16_f32 v125, v90, v91
	ds_read_b64_tr_b16 v[2:3], v4 offset:31744
	ds_read_b64_tr_b16 v[4:5], v4 offset:32256
	v_mfma_f32_32x32x16_bf16 v[48:63], v[144:147], v[112:115], v[48:63]
	v_add_f32_e32 v80, v94, v80
	v_add_f32_e32 v80, v95, v80
	v_add_f32_e32 v80, 0, v80
	v_cvt_pk_bf16_f32 v126, v92, v93
	v_cvt_pk_bf16_f32 v127, v94, v95
	s_add_i32 s45, s17, 2
	s_cmp_ge_i32 s45, s61
	s_cselect_b64 s[14:15], -1, 0
	s_and_b64 vcc, exec, s[14:15]
	s_cbranch_vccnz .LBB0_510
	s_add_i32 s6, s63, s39
	s_mov_b32 s7, m0
	s_mov_b32 m0, s6
	s_nop 0
	global_load_lds_dwordx4 v[188:189], off
	s_mov_b32 m0, s7

.LBB0_546:
	v_lshl_add_u32 v1, s60, 2, v200
	v_add_u32_e32 v2, 0xffffff00, v1
	v_add_u32_e32 v6, 0xffffff80, v1
	v_add_u32_e32 v10, 0xffffff20, v1
	v_add_u32_e32 v14, 0xffffffa0, v1
	ds_read_b128 v[2:5], v2
	ds_read_b128 v[6:9], v6
	ds_read_b128 v[10:13], v10
	ds_read_b128 v[96:99], v14
	v_add_u32_e32 v14, 0xffffff40, v1
	v_subrev_u32_e32 v15, 64, v1
	v_add_u32_e32 v80, 0xffffff60, v1
	v_subrev_u32_e32 v1, 32, v1
	ds_read_b128 v[80:83], v80
	ds_read_b128 v[84:87], v14
	ds_read_b128 v[100:103], v15
	ds_read_b128 v[104:107], v1
	s_waitcnt lgkmcnt(3)
	v_xor_b32_e32 v240, 0x80000000, v201
	v_pk_add_f32 v[94:95], v[82:83], v[240:241] op_sel_hi:[1,0]
	v_pk_add_f32 v[92:93], v[80:81], v[240:241] op_sel_hi:[1,0]
	s_waitcnt lgkmcnt(2)
	v_pk_add_f32 v[90:91], v[86:87], v[240:241] op_sel_hi:[1,0]
	v_pk_add_f32 v[88:89], v[84:85], v[240:241] op_sel_hi:[1,0]
	v_pk_add_f32 v[86:87], v[12:13], v[240:241] op_sel_hi:[1,0]
	v_pk_add_f32 v[84:85], v[10:11], v[240:241] op_sel_hi:[1,0]
	v_pk_add_f32 v[82:83], v[4:5], v[240:241] op_sel_hi:[1,0]
	v_pk_add_f32 v[80:81], v[2:3], v[240:241] op_sel_hi:[1,0]
	s_waitcnt lgkmcnt(0)
	v_pk_add_f32 v[110:111], v[106:107], v[240:241] op_sel_hi:[1,0]
	v_pk_add_f32 v[108:109], v[104:105], v[240:241] op_sel_hi:[1,0]
	v_pk_add_f32 v[106:107], v[102:103], v[240:241] op_sel_hi:[1,0]
	v_pk_add_f32 v[104:105], v[100:101], v[240:241] op_sel_hi:[1,0]
	v_pk_add_f32 v[102:103], v[98:99], v[240:241] op_sel_hi:[1,0]
	v_pk_add_f32 v[100:101], v[96:97], v[240:241] op_sel_hi:[1,0]
	v_pk_add_f32 v[98:99], v[8:9], v[240:241] op_sel_hi:[1,0]
	v_pk_add_f32 v[96:97], v[6:7], v[240:241] op_sel_hi:[1,0]
	v_add_u32_e32 v1, s63, v199
	ds_read_b64_tr_b16 v[2:3], v1 offset:24576
	ds_read_b64_tr_b16 v[4:5], v1 offset:25088
	v_mfma_f32_32x32x16_bf16 v[80:95], v[172:175], v[132:135], v[80:95]
	v_add_f32_e32 v6, v64, v65
	v_add_f32_e32 v6, v66, v6
	v_add_f32_e32 v6, v67, v6
	v_add_f32_e32 v6, v68, v6
	v_add_f32_e32 v10, v69, v6
	v_cvt_pk_bf16_f32 v140, v64, v65
	v_cvt_pk_bf16_f32 v141, v66, v67
	ds_read_b64_tr_b16 v[6:7], v1 offset:28672
	ds_read_b64_tr_b16 v[8:9], v1 offset:29184
	v_mfma_f32_32x32x16_bf16 v[96:111], v[168:171], v[132:135], v[96:111]
	v_add_f32_e32 v10, v70, v10
	v_add_f32_e32 v10, v71, v10
	v_add_f32_e32 v10, v72, v10
	v_add_f32_e32 v14, v73, v10
	v_cvt_pk_bf16_f32 v142, v68, v69
	v_cvt_pk_bf16_f32 v143, v70, v71
	ds_read_b64_tr_b16 v[10:11], v1 offset:25600
	ds_read_b64_tr_b16 v[12:13], v1 offset:26112
	v_mfma_f32_32x32x16_bf16 v[80:95], v[164:167], v[120:123], v[80:95]
	v_add_f32_e32 v14, v74, v14
	v_add_f32_e32 v14, v75, v14
	v_add_f32_e32 v14, v76, v14
	v_add_f32_e32 v14, v77, v14
	v_cvt_pk_bf16_f32 v136, v72, v73
	v_cvt_pk_bf16_f32 v137, v74, v75
	ds_read_b64_tr_b16 v[64:65], v1 offset:29696
	ds_read_b64_tr_b16 v[66:67], v1 offset:30208
	v_mfma_f32_32x32x16_bf16 v[96:111], v[160:163], v[120:123], v[96:111]
	v_add_f32_e32 v14, v78, v14
	v_add_f32_e32 v14, v79, v14
	v_add_f32_e32 v14, v48, v14
	v_add_f32_e32 v14, v49, v14
	v_cvt_pk_bf16_f32 v138, v76, v77
	v_cvt_pk_bf16_f32 v139, v78, v79
	ds_read_b64_tr_b16 v[68:69], v1 offset:26624
	ds_read_b64_tr_b16 v[70:71], v1 offset:27136
	v_mfma_f32_32x32x16_bf16 v[80:95], v[156:159], v[116:119], v[80:95]
	v_add_f32_e32 v14, v50, v14
	v_add_f32_e32 v14, v51, v14
	v_add_f32_e32 v14, v52, v14
	v_add_f32_e32 v14, v53, v14
	v_cvt_pk_bf16_f32 v128, v48, v49
	v_cvt_pk_bf16_f32 v129, v50, v51
	ds_read_b64_tr_b16 v[48:49], v1 offset:30720
	ds_read_b64_tr_b16 v[50:51], v1 offset:31232
	v_mfma_f32_32x32x16_bf16 v[96:111], v[152:155], v[116:119], v[96:111]
	v_add_f32_e32 v14, v54, v14
	v_add_f32_e32 v14, v55, v14
	v_add_f32_e32 v14, v56, v14
	v_add_f32_e32 v14, v57, v14
	v_cvt_pk_bf16_f32 v130, v52, v53
	v_cvt_pk_bf16_f32 v131, v54, v55
	ds_read_b64_tr_b16 v[52:53], v1 offset:27648
	ds_read_b64_tr_b16 v[54:55], v1 offset:28160
	v_mfma_f32_32x32x16_bf16 v[80:95], v[148:151], v[112:115], v[80:95]
	v_add_f32_e32 v14, v58, v14
	v_add_f32_e32 v14, v59, v14
	v_add_f32_e32 v14, v60, v14
	v_add_f32_e32 v14, v61, v14
	v_cvt_pk_bf16_f32 v124, v56, v57
	v_cvt_pk_bf16_f32 v125, v58, v59
	ds_read_b64_tr_b16 v[56:57], v1 offset:31744
	ds_read_b64_tr_b16 v[58:59], v1 offset:32256
	v_mfma_f32_32x32x16_bf16 v[96:111], v[144:147], v[112:115], v[96:111]
	v_add_f32_e32 v1, v62, v14
	v_add_f32_e32 v1, v63, v1
	v_add_f32_e32 v1, 0, v1
	v_cvt_pk_bf16_f32 v126, v60, v61
	v_cvt_pk_bf16_f32 v127, v62, v63
	v_max_f32_e32 v14, v81, v81
	v_max_f32_e32 v15, v80, v80
	v_max_f32_e32 v14, v15, v14
	s_nop 3
	v_max3_f32 v15, v82, v83, v97
	v_max3_f32 v14, v14, v96, v98
	v_max3_f32 v14, v14, v99, v84
	v_max3_f32 v15, v15, v86, v87
	v_max3_f32 v14, v14, v85, v100
	v_max3_f32 v15, v15, v102, v103
	v_max3_f32 v14, v14, v101, v88
	v_max3_f32 v15, v15, v90, v91
	v_max3_f32 v14, v14, v89, v104
	v_max3_f32 v15, v15, v106, v107
	v_max3_f32 v14, v14, v105, v92
	v_max3_f32 v15, v15, v94, v95
	v_max3_f32 v14, v14, v93, v108
	v_max3_f32 v15, v15, v110, v111
	v_max3_f32 v14, v14, v109, v15
	v_mov_b32_e32 v15, v14
	s_nop 1
	v_permlane32_swap_b32_e32 v14, v15
	v_max_f32_e32 v15, v15, v15
	v_max_f32_e32 v14, v14, v14
	v_max_f32_e32 v14, v14, v15
	v_cmp_lt_f32_e32 vcc, s96, v14
	s_cmp_lg_u64 vcc, 0
	v_add_f32_e32 v1, v203, v1
	s_cselect_b64 s[4:5], -1, 0
	s_cbranch_vccnz .LBB0_559
